# nt hint on all 28 weight-transpose stores of P0 (the previous version covered 8)
# baseline (speedup 1.0000x reference)
; __device__ __forceinline__ void transpose_item(const float* W, int K, int N, bf16_t* WT, int ldt, int k0, int n0, int drow0, LAS float* scr, int lane,
;                                                const float* gam = nullptr, const float* bet = nullptr, float* csp = nullptr, float* bcp = nullptr) {
;     float tv[32];
; #pragma unroll
;     for (int i = 0; i < 32; ++i) tv[i] = __builtin_nontemporal_load(W + (size_t)(k0 + 2 * i + (lane >> 5)) * N + n0 + (lane & 31));
; #pragma unroll
;     for (int i = 0; i < 32; ++i) scr[(2 * i + (lane >> 5)) * 33 + (lane & 31)] = tv[i];
; __device__ __forceinline__ void p0_prologue(const Params& p, const Frame& F0) {
;     ...
;         if (r < I_IN) { const int kb = r / 48, nb = r % 48; transpose_item(p.in[8], DM, DIN, Win_t, DM, 64 * kb, 32 * nb, win_dest_row(32 * nb), scr, F.lane); continue; } r -= I_IN;
.LBB0_9:
	s_lshl_b32 s4, s21, 6
	v_or_b32_e32 v37, s4, v9
	s_ashr_i32 s21, s20, 31
	s_waitcnt lgkmcnt(1)
	v_lshl_add_u64 v[2:3], s[20:21], 2, v[32:33]
	v_or_b32_e32 v53, 12, v37
	v_or_b32_e32 v38, 2, v37
	v_or_b32_e32 v40, 4, v37
	v_or_b32_e32 v42, 6, v37
	v_or_b32_e32 v44, 8, v37
	v_or_b32_e32 v46, 10, v37
	v_mad_i64_i32 v[54:55], s[20:21], v53, s38, v[2:3]
	v_or_b32_e32 v53, 14, v37
	s_waitcnt lgkmcnt(0)
	v_mad_i64_i32 v[4:5], s[20:21], v37, s38, v[2:3]
	v_mad_i64_i32 v[38:39], s[20:21], v38, s38, v[2:3]
	v_mad_i64_i32 v[40:41], s[20:21], v40, s38, v[2:3]
	v_mad_i64_i32 v[42:43], s[20:21], v42, s38, v[2:3]
	v_mad_i64_i32 v[44:45], s[20:21], v44, s38, v[2:3]
	v_mad_i64_i32 v[46:47], s[20:21], v46, s38, v[2:3]
	v_mad_i64_i32 v[56:57], s[20:21], v53, s38, v[2:3]
	global_load_dword v53, v[4:5], off nt
	global_load_dword v58, v[38:39], off nt
	global_load_dword v59, v[40:41], off nt
	global_load_dword v60, v[42:43], off nt
	global_load_dword v61, v[44:45], off nt
	global_load_dword v62, v[46:47], off nt
	global_load_dword v63, v[54:55], off nt
	global_load_dword v64, v[56:57], off nt
	v_or_b32_e32 v4, 16, v37
	v_or_b32_e32 v38, 18, v37
	v_or_b32_e32 v40, 20, v37
	v_or_b32_e32 v42, 22, v37
	v_or_b32_e32 v44, 24, v37
	v_or_b32_e32 v46, 26, v37
	v_or_b32_e32 v54, 28, v37
	v_or_b32_e32 v56, 30, v37
	v_mad_i64_i32 v[4:5], s[20:21], v4, s38, v[2:3]
	v_mad_i64_i32 v[38:39], s[20:21], v38, s38, v[2:3]
	v_mad_i64_i32 v[40:41], s[20:21], v40, s38, v[2:3]
	v_mad_i64_i32 v[42:43], s[20:21], v42, s38, v[2:3]
	v_mad_i64_i32 v[44:45], s[20:21], v44, s38, v[2:3]
	v_mad_i64_i32 v[46:47], s[20:21], v46, s38, v[2:3]
	v_mad_i64_i32 v[54:55], s[20:21], v54, s38, v[2:3]
	v_mad_i64_i32 v[56:57], s[20:21], v56, s38, v[2:3]
	global_load_dword v65, v[4:5], off nt
	global_load_dword v66, v[38:39], off nt
	global_load_dword v67, v[40:41], off nt
	global_load_dword v68, v[42:43], off nt
	global_load_dword v69, v[44:45], off nt
	global_load_dword v70, v[46:47], off nt
	global_load_dword v71, v[54:55], off nt
	global_load_dword v72, v[56:57], off nt
	v_or_b32_e32 v4, 32, v37
	v_or_b32_e32 v38, 34, v37
	v_or_b32_e32 v40, 36, v37
	v_or_b32_e32 v42, 38, v37
	v_or_b32_e32 v44, 40, v37
	v_or_b32_e32 v46, 42, v37
	v_or_b32_e32 v54, 44, v37
	v_or_b32_e32 v56, 46, v37
	v_mad_i64_i32 v[4:5], s[20:21], v4, s38, v[2:3]
	v_mad_i64_i32 v[38:39], s[20:21], v38, s38, v[2:3]
	v_mad_i64_i32 v[40:41], s[20:21], v40, s38, v[2:3]
	v_mad_i64_i32 v[42:43], s[20:21], v42, s38, v[2:3]
	v_mad_i64_i32 v[44:45], s[20:21], v44, s38, v[2:3]
	v_mad_i64_i32 v[46:47], s[20:21], v46, s38, v[2:3]
	v_mad_i64_i32 v[54:55], s[20:21], v54, s38, v[2:3]
	v_mad_i64_i32 v[56:57], s[20:21], v56, s38, v[2:3]
	global_load_dword v73, v[4:5], off nt
	global_load_dword v74, v[38:39], off nt
	global_load_dword v75, v[40:41], off nt
	global_load_dword v76, v[42:43], off nt
	global_load_dword v77, v[44:45], off nt
	global_load_dword v78, v[46:47], off nt
	global_load_dword v79, v[54:55], off nt
	s_nop 0
	global_load_dword v56, v[56:57], off nt
	v_or_b32_e32 v4, 48, v37
	v_or_b32_e32 v38, 50, v37
	v_or_b32_e32 v40, 52, v37
	v_or_b32_e32 v42, 54, v37
	v_or_b32_e32 v44, 56, v37
	v_or_b32_e32 v46, 58, v37
	v_or_b32_e32 v54, 60, v37
	v_or_b32_e32 v37, 62, v37
	v_mad_i64_i32 v[4:5], s[20:21], v4, s38, v[2:3]
	v_mad_i64_i32 v[38:39], s[20:21], v38, s38, v[2:3]
	v_mad_i64_i32 v[40:41], s[20:21], v40, s38, v[2:3]
	v_mad_i64_i32 v[42:43], s[20:21], v42, s38, v[2:3]
	v_mad_i64_i32 v[44:45], s[20:21], v44, s38, v[2:3]
	v_mad_i64_i32 v[46:47], s[20:21], v46, s38, v[2:3]
	v_mad_i64_i32 v[54:55], s[20:21], v54, s38, v[2:3]
	v_mad_i64_i32 v[2:3], s[20:21], v37, s38, v[2:3]
	global_load_dword v4, v[4:5], off nt
	s_nop 0
	global_load_dword v5, v[38:39], off nt
	global_load_dword v37, v[40:41], off nt
	s_nop 0
	global_load_dword v38, v[42:43], off nt
	global_load_dword v39, v[44:45], off nt
	global_load_dword v40, v[46:47], off nt
	global_load_dword v41, v[54:55], off nt
	s_nop 0
	global_load_dword v2, v[2:3], off nt
	s_waitcnt vmcnt(30)
; #define LAS __attribute__((address_space(3)))
; __device__ __forceinline__ unsigned cvt_pk_bf16(float lo, float hi) { unsigned r; asm("v_cvt_pk_bf16_f32 %0, %1, %2" : "=v"(r) : "v"(lo), "v"(hi)); return r; }
; __device__ __forceinline__ void transpose_item(const float* W, int K, int N, bf16_t* WT, int ldt, int k0, int n0, int drow0, LAS float* scr, int lane,
;                                                const float* gam = nullptr, const float* bet = nullptr, float* csp = nullptr, float* bcp = nullptr) {
;     ...
;     for (int i = 0; i < 32; ++i) scr[(2 * i + (lane >> 5)) * 33 + (lane & 31)] = tv[i];
;     asm volatile("s_waitcnt lgkmcnt(0)" ::: "memory");
;     const int c = lane & 7;
;     float ge[8], be[8];
; #pragma unroll
;     for (int e = 0; e < 8; ++e) { ge[e] = gam ? gam[k0 + 8 * c + e] : 1.f; be[e] = gam ? bet[k0 + 8 * c + e] : 0.f; }
; #pragma unroll
;     for (int j = 0; j < 4; ++j) { const int n = (lane >> 3) + 8 * j; const LAS float* sp = scr + (8 * c) * 33 + n;
;         float w[8];
; #pragma unroll
;         for (int e = 0; e < 8; ++e) w[e] = sp[e * 33];
;         u32x4 o; o.x = cvt_pk_bf16(w[0] * ge[0], w[1] * ge[1]); o.y = cvt_pk_bf16(w[2] * ge[2], w[3] * ge[3]); o.z = cvt_pk_bf16(w[4] * ge[4], w[5] * ge[5]); o.w = cvt_pk_bf16(w[6] * ge[6], w[7] * ge[7]);
;         *(u32x4*)(WT + (size_t)(drow0 + n) * ldt + k0 + 8 * c) = o;
	ds_write2_b32 v11, v53, v58 offset1:66
	s_waitcnt vmcnt(28)
	ds_write2_b32 v11, v59, v60 offset0:132 offset1:198
	s_waitcnt vmcnt(26)
	ds_write2_b32 v15, v61, v62 offset0:8 offset1:74
	s_waitcnt vmcnt(24)
	ds_write2_b32 v15, v63, v64 offset0:140 offset1:206
	s_waitcnt vmcnt(22)
	ds_write2_b32 v17, v65, v66 offset0:16 offset1:82
	s_waitcnt vmcnt(20)
	ds_write2_b32 v17, v67, v68 offset0:148 offset1:214
	s_waitcnt vmcnt(18)
	ds_write2_b32 v35, v69, v70 offset0:24 offset1:90
	s_waitcnt vmcnt(16)
	ds_write2_b32 v35, v71, v72 offset0:156 offset1:222
	s_waitcnt vmcnt(14)
	ds_write2_b32 v48, v73, v74 offset0:32 offset1:98
	s_waitcnt vmcnt(12)
	ds_write2_b32 v48, v75, v76 offset0:164 offset1:230
	s_waitcnt vmcnt(10)
	ds_write2_b32 v49, v77, v78 offset0:40 offset1:106
	s_waitcnt vmcnt(8)
	ds_write2_b32 v49, v79, v56 offset0:172 offset1:238
	s_waitcnt vmcnt(6)
	ds_write2_b32 v50, v4, v5 offset0:48 offset1:114
	s_waitcnt vmcnt(4)
	ds_write2_b32 v50, v37, v38 offset0:180 offset1:246
	s_waitcnt vmcnt(2)
	ds_write2_b32 v51, v39, v40 offset0:56 offset1:122
	s_waitcnt vmcnt(0)
	ds_write2_b32 v51, v41, v2 offset0:188 offset1:254
	s_waitcnt lgkmcnt(0)
	ds_read2_b32 v[38:39], v13 offset1:8
	ds_read2_b32 v[40:41], v13 offset0:33 offset1:41
	ds_read2_b32 v[42:43], v13 offset0:66 offset1:74
	ds_read2_b32 v[44:45], v13 offset0:99 offset1:107
	ds_read2_b32 v[46:47], v13 offset0:132 offset1:140
	ds_read2_b32 v[54:55], v13 offset0:165 offset1:173
	ds_read2_b32 v[56:57], v13 offset0:198 offset1:206
	ds_read2_b32 v[58:59], v13 offset0:231 offset1:239
	v_add_u32_e32 v62, s18, v10
	s_ashr_i32 s5, s4, 31
	v_ashrrev_i32_e32 v63, 31, v62
	v_lshl_add_u64 v[60:61], s[4:5], 1, v[24:25]
	v_lshlrev_b64 v[62:63], 11, v[62:63]
	s_waitcnt lgkmcnt(6)
	v_cvt_pk_bf16_f32 v2, v38, v40
	v_lshl_add_u64 v[62:63], v[60:61], 0, v[62:63]
	v_add_u32_e32 v38, s18, v12
	s_waitcnt lgkmcnt(4)
	v_cvt_pk_bf16_f32 v3, v42, v44
	s_waitcnt lgkmcnt(2)
	v_cvt_pk_bf16_f32 v4, v46, v54
	s_waitcnt lgkmcnt(0)
	v_cvt_pk_bf16_f32 v5, v56, v58
	global_store_dwordx4 v[62:63], v[2:5], off nt
	s_nop 1
	v_cvt_pk_bf16_f32 v2, v39, v41
	v_ashrrev_i32_e32 v39, 31, v38
	v_lshlrev_b64 v[38:39], 11, v[38:39]
	v_cvt_pk_bf16_f32 v3, v43, v45
	v_cvt_pk_bf16_f32 v4, v47, v55
	v_cvt_pk_bf16_f32 v5, v57, v59
	v_lshl_add_u64 v[38:39], v[60:61], 0, v[38:39]
	ds_read2_b32 v[40:41], v13 offset0:16 offset1:24
	ds_read2_b32 v[42:43], v13 offset0:49 offset1:57
	ds_read2_b32 v[44:45], v13 offset0:82 offset1:90
	ds_read2_b32 v[46:47], v13 offset0:115 offset1:123
	ds_read2_b32 v[54:55], v13 offset0:148 offset1:156
	ds_read2_b32 v[56:57], v13 offset0:181 offset1:189
	ds_read2_b32 v[58:59], v13 offset0:214 offset1:222
	ds_read2_b32 v[62:63], v13 offset0:247 offset1:255
	global_store_dwordx4 v[38:39], v[2:5], off nt
	v_add_u32_e32 v38, s18, v14
	v_ashrrev_i32_e32 v39, 31, v38
	v_lshlrev_b64 v[38:39], 11, v[38:39]
	v_lshl_add_u64 v[38:39], v[60:61], 0, v[38:39]
	s_waitcnt lgkmcnt(6)
	v_cvt_pk_bf16_f32 v2, v40, v42
	s_waitcnt lgkmcnt(4)
	v_cvt_pk_bf16_f32 v3, v44, v46
	s_waitcnt lgkmcnt(2)
	v_cvt_pk_bf16_f32 v4, v54, v56
	s_waitcnt lgkmcnt(0)
	v_cvt_pk_bf16_f32 v5, v58, v62
	global_store_dwordx4 v[38:39], v[2:5], off nt
	v_add_u32_e32 v38, s18, v16
	v_ashrrev_i32_e32 v39, 31, v38
	v_lshlrev_b64 v[38:39], 11, v[38:39]
	v_lshl_add_u64 v[38:39], v[60:61], 0, v[38:39]
	v_cvt_pk_bf16_f32 v2, v41, v43
	v_cvt_pk_bf16_f32 v3, v45, v47
	v_cvt_pk_bf16_f32 v4, v55, v57
	v_cvt_pk_bf16_f32 v5, v59, v63
	global_store_dwordx4 v[38:39], v[2:5], off nt
	s_waitcnt lgkmcnt(0)

; __device__ __forceinline__ void transpose_item(const float* W, int K, int N, bf16_t* WT, int ldt, int k0, int n0, int drow0, LAS float* scr, int lane,
;                                                const float* gam = nullptr, const float* bet = nullptr, float* csp = nullptr, float* bcp = nullptr) {
;     float tv[32];
; #pragma unroll
;     for (int i = 0; i < 32; ++i) tv[i] = __builtin_nontemporal_load(W + (size_t)(k0 + 2 * i + (lane >> 5)) * N + n0 + (lane & 31));
; #pragma unroll
;     for (int i = 0; i < 32; ++i) scr[(2 * i + (lane >> 5)) * 33 + (lane & 31)] = tv[i];
; __device__ __forceinline__ void p0_prologue(const Params& p, const Frame& F0) {
;     ...
;         if (r < I_2) { const int kb = r / 32, nb = r % 32; transpose_item(p.in[34], DFF, DM, W2_t, DFF, 64 * kb, 32 * nb, 32 * nb, scr, F.lane); continue; } r -= I_2;
;         { const int js = r / 128, q = r % 128, kb = q / 32, nb = q % 32;
;           transpose_item(p.in[6] + (size_t)js * NMEM * DM, NMEM, DM, Vt + (size_t)(2 + js) * DM * NMEM, NMEM, 64 * kb, 32 * nb, 32 * nb, scr, F.lane); }
.LBB0_11:
	s_cmpk_gt_i32 s26, 0x2ff
	s_mov_b64 s[4:5], -1
	s_cbranch_scc0 .LBB0_150
	s_cmpk_gt_u32 s26, 0x37f
	s_cbranch_scc0 .LBB0_147
	s_cmpk_gt_u32 s26, 0xd7f
	s_cbranch_scc0 .LBB0_72
	s_cmpk_gt_u32 s26, 0x157f
	s_cbranch_scc0 .LBB0_20
	s_cmpk_gt_u32 s26, 0x1d7f
	s_cbranch_scc0 .LBB0_17
	s_add_i32 s4, s26, 0xffffe280
	s_lshr_b32 s18, s4, 7
	v_readlane_b32 s76, v254, 22
	s_lshl_b64 s[4:5], s[18:19], 20
	v_readlane_b32 s88, v254, 34
	v_readlane_b32 s89, v254, 35
	s_add_u32 s22, s88, s4
	s_addc_u32 s23, s89, s5
	s_add_i32 s18, s18, 2
	s_lshl_b64 s[20:21], s[18:19], 19
	v_readlane_b32 s4, v254, 54
	s_add_u32 s5, s4, s20
	v_readlane_b32 s4, v254, 55
	s_addc_u32 s18, s4, s21
	s_and_b32 s4, s27, 0x3e0
	s_and_b32 s20, s31, 0xc0
	s_lshl_b32 s21, s4, 2
	s_add_u32 s22, s22, s21
	v_or_b32_e32 v4, s20, v9
	s_addc_u32 s23, s23, 0
	v_mov_b32_e32 v37, v7
	s_waitcnt lgkmcnt(1)
	v_lshl_add_u64 v[2:3], s[22:23], 0, v[36:37]
	v_lshlrev_b32_e32 v4, 12, v4
	s_waitcnt lgkmcnt(0)
	v_mov_b32_e32 v5, v7
	v_lshl_add_u64 v[2:3], v[2:3], 0, v[4:5]
	v_add_co_u32_e32 v4, vcc, s14, v2
	s_mov_b32 s21, 0x22000
	s_nop 0
	v_addc_co_u32_e32 v5, vcc, 0, v3, vcc
	v_add_co_u32_e32 v38, vcc, s15, v2
	s_lshl_b32 s20, s20, 1
	s_nop 0
	v_addc_co_u32_e32 v39, vcc, 0, v3, vcc
	v_add_co_u32_e32 v40, vcc, s63, v2
	s_add_u32 s20, s5, s20
	s_nop 0
	v_addc_co_u32_e32 v41, vcc, 0, v3, vcc
	v_add_co_u32_e32 v42, vcc, s64, v2
	v_readlane_b32 s77, v254, 23
	s_nop 0
	v_addc_co_u32_e32 v43, vcc, 0, v3, vcc
	v_add_co_u32_e32 v44, vcc, s65, v2
	v_readlane_b32 s78, v254, 24
	s_nop 0
	v_addc_co_u32_e32 v45, vcc, 0, v3, vcc
	v_add_co_u32_e32 v46, vcc, s66, v2
	v_readlane_b32 s79, v254, 25
	s_nop 0
	v_addc_co_u32_e32 v47, vcc, 0, v3, vcc
	v_add_co_u32_e32 v54, vcc, s67, v2
	v_readlane_b32 s80, v254, 26
	s_nop 0
	v_addc_co_u32_e32 v55, vcc, 0, v3, vcc
	global_load_dword v37, v[2:3], off nt
	global_load_dword v53, v[4:5], off nt
	global_load_dword v58, v[38:39], off nt
	global_load_dword v59, v[40:41], off nt
	global_load_dword v60, v[42:43], off nt
	global_load_dword v61, v[44:45], off nt
	global_load_dword v62, v[46:47], off nt
	global_load_dword v63, v[54:55], off nt
	v_add_co_u32_e32 v4, vcc, s68, v2
	v_readlane_b32 s81, v254, 27
	s_nop 0
	v_addc_co_u32_e32 v5, vcc, 0, v3, vcc
	v_add_co_u32_e32 v38, vcc, s69, v2
	v_readlane_b32 s82, v254, 28
	s_nop 0
	v_addc_co_u32_e32 v39, vcc, 0, v3, vcc
	v_add_co_u32_e32 v40, vcc, s70, v2
	v_readlane_b32 s83, v254, 29
	s_nop 0
	v_addc_co_u32_e32 v41, vcc, 0, v3, vcc
	v_add_co_u32_e32 v42, vcc, s71, v2
	v_readlane_b32 s84, v254, 30
	s_nop 0
	v_addc_co_u32_e32 v43, vcc, 0, v3, vcc
	v_add_co_u32_e32 v44, vcc, s72, v2
	v_readlane_b32 s85, v254, 31
	s_nop 0
	v_addc_co_u32_e32 v45, vcc, 0, v3, vcc
	v_add_co_u32_e32 v46, vcc, s73, v2
	v_readlane_b32 s86, v254, 32
	s_nop 0
	v_addc_co_u32_e32 v47, vcc, 0, v3, vcc
	v_add_co_u32_e32 v54, vcc, s74, v2
	v_readlane_b32 s87, v254, 33
	s_nop 0
	v_addc_co_u32_e32 v55, vcc, 0, v3, vcc
	v_add_co_u32_e32 v56, vcc, s75, v2
	v_readlane_b32 s90, v254, 36
	s_nop 0
	v_addc_co_u32_e32 v57, vcc, 0, v3, vcc
	global_load_dword v64, v[4:5], off nt
	global_load_dword v65, v[38:39], off nt
	global_load_dword v66, v[40:41], off nt
	global_load_dword v67, v[42:43], off nt
	global_load_dword v68, v[44:45], off nt
	global_load_dword v69, v[46:47], off nt
	global_load_dword v70, v[54:55], off nt
	global_load_dword v71, v[56:57], off nt
	v_add_co_u32_e32 v4, vcc, s94, v2
	v_readlane_b32 s91, v254, 37
	s_nop 0
	v_addc_co_u32_e32 v5, vcc, 0, v3, vcc
	v_add_co_u32_e32 v38, vcc, s21, v2
	s_mov_b32 s21, 0x24000
	s_nop 0
	v_addc_co_u32_e32 v39, vcc, 0, v3, vcc
	v_add_co_u32_e32 v40, vcc, s21, v2
	s_addc_u32 s21, s18, 0
	s_nop 0
	v_addc_co_u32_e32 v41, vcc, 0, v3, vcc
	v_add_co_u32_e32 v42, vcc, s12, v2
	s_nop 1
	v_addc_co_u32_e32 v43, vcc, 0, v3, vcc
	v_add_co_u32_e32 v44, vcc, s13, v2
	s_nop 1
	v_addc_co_u32_e32 v45, vcc, 0, v3, vcc
	v_add_co_u32_e32 v46, vcc, s42, v2
	s_nop 1
	v_addc_co_u32_e32 v47, vcc, 0, v3, vcc
	v_add_co_u32_e32 v54, vcc, s43, v2
	s_nop 1
	v_addc_co_u32_e32 v55, vcc, 0, v3, vcc
	v_add_co_u32_e32 v56, vcc, s44, v2
	s_nop 1
	v_addc_co_u32_e32 v57, vcc, 0, v3, vcc
	global_load_dword v72, v[4:5], off nt
	global_load_dword v73, v[38:39], off nt
	global_load_dword v74, v[40:41], off nt
	global_load_dword v75, v[42:43], off nt
	global_load_dword v76, v[44:45], off nt
	global_load_dword v77, v[46:47], off nt
	global_load_dword v78, v[54:55], off nt
	s_nop 0
	global_load_dword v56, v[56:57], off nt
	v_add_co_u32_e32 v4, vcc, s45, v2
	s_nop 1
	v_addc_co_u32_e32 v5, vcc, 0, v3, vcc
	v_add_co_u32_e32 v38, vcc, s48, v2
	s_nop 1
	v_addc_co_u32_e32 v39, vcc, 0, v3, vcc
	v_add_co_u32_e32 v40, vcc, s49, v2
	s_nop 1
	v_addc_co_u32_e32 v41, vcc, 0, v3, vcc
	v_add_co_u32_e32 v42, vcc, s60, v2
	s_nop 1
	v_addc_co_u32_e32 v43, vcc, 0, v3, vcc
	v_add_co_u32_e32 v44, vcc, s61, v2
	s_nop 1
	v_addc_co_u32_e32 v45, vcc, 0, v3, vcc
	v_add_co_u32_e32 v46, vcc, s95, v2
	s_nop 1
	v_addc_co_u32_e32 v47, vcc, 0, v3, vcc
	v_add_co_u32_e32 v54, vcc, s3, v2
	s_nop 1
	v_addc_co_u32_e32 v55, vcc, 0, v3, vcc
	v_add_co_u32_e32 v2, vcc, s37, v2
	s_nop 1
	v_addc_co_u32_e32 v3, vcc, 0, v3, vcc
	global_load_dword v4, v[4:5], off nt
	s_nop 0
	global_load_dword v5, v[38:39], off nt
	s_nop 0
	global_load_dword v38, v[40:41], off nt
	global_load_dword v39, v[42:43], off nt
	s_nop 0
	global_load_dword v40, v[44:45], off nt
	global_load_dword v41, v[46:47], off nt
	global_load_dword v42, v[54:55], off nt
	s_nop 0
	global_load_dword v2, v[2:3], off nt
	s_waitcnt vmcnt(30)
	ds_write2_b32 v11, v37, v53 offset1:66
	s_waitcnt vmcnt(28)
	ds_write2_b32 v11, v58, v59 offset0:132 offset1:198
	s_waitcnt vmcnt(26)
; #define LAS __attribute__((address_space(3)))
; __device__ __forceinline__ unsigned cvt_pk_bf16(float lo, float hi) { unsigned r; asm("v_cvt_pk_bf16_f32 %0, %1, %2" : "=v"(r) : "v"(lo), "v"(hi)); return r; }
; __device__ __forceinline__ void transpose_item(const float* W, int K, int N, bf16_t* WT, int ldt, int k0, int n0, int drow0, LAS float* scr, int lane,
;                                                const float* gam = nullptr, const float* bet = nullptr, float* csp = nullptr, float* bcp = nullptr) {
;     ...
;     for (int i = 0; i < 32; ++i) scr[(2 * i + (lane >> 5)) * 33 + (lane & 31)] = tv[i];
;     asm volatile("s_waitcnt lgkmcnt(0)" ::: "memory");
;     const int c = lane & 7;
;     float ge[8], be[8];
; #pragma unroll
;     for (int e = 0; e < 8; ++e) { ge[e] = gam ? gam[k0 + 8 * c + e] : 1.f; be[e] = gam ? bet[k0 + 8 * c + e] : 0.f; }
; #pragma unroll
;     for (int j = 0; j < 4; ++j) { const int n = (lane >> 3) + 8 * j; const LAS float* sp = scr + (8 * c) * 33 + n;
;         float w[8];
; #pragma unroll
;         for (int e = 0; e < 8; ++e) w[e] = sp[e * 33];
;         u32x4 o; o.x = cvt_pk_bf16(w[0] * ge[0], w[1] * ge[1]); o.y = cvt_pk_bf16(w[2] * ge[2], w[3] * ge[3]); o.z = cvt_pk_bf16(w[4] * ge[4], w[5] * ge[5]); o.w = cvt_pk_bf16(w[6] * ge[6], w[7] * ge[7]);
;         *(u32x4*)(WT + (size_t)(drow0 + n) * ldt + k0 + 8 * c) = o;
; __device__ __forceinline__ void p0_prologue(const Params& p, const Frame& F0) {
;     ...
;         if (r < I_2) { const int kb = r / 32, nb = r % 32; transpose_item(p.in[34], DFF, DM, W2_t, DFF, 64 * kb, 32 * nb, 32 * nb, scr, F.lane); continue; } r -= I_2;
	ds_write2_b32 v15, v60, v61 offset0:8 offset1:74
	s_waitcnt vmcnt(24)
	ds_write2_b32 v15, v62, v63 offset0:140 offset1:206
	s_waitcnt vmcnt(22)
	ds_write2_b32 v17, v64, v65 offset0:16 offset1:82
	s_waitcnt vmcnt(20)
	ds_write2_b32 v17, v66, v67 offset0:148 offset1:214
	s_waitcnt vmcnt(18)
	ds_write2_b32 v35, v68, v69 offset0:24 offset1:90
	s_waitcnt vmcnt(16)
	ds_write2_b32 v35, v70, v71 offset0:156 offset1:222
	s_waitcnt vmcnt(14)
	ds_write2_b32 v48, v72, v73 offset0:32 offset1:98
	s_waitcnt vmcnt(12)
	ds_write2_b32 v48, v74, v75 offset0:164 offset1:230
	s_waitcnt vmcnt(10)
	ds_write2_b32 v49, v76, v77 offset0:40 offset1:106
	s_waitcnt vmcnt(8)
	ds_write2_b32 v49, v78, v56 offset0:172 offset1:238
	s_waitcnt vmcnt(6)
	ds_write2_b32 v50, v4, v5 offset0:48 offset1:114
	s_waitcnt vmcnt(4)
	ds_write2_b32 v50, v38, v39 offset0:180 offset1:246
	s_waitcnt vmcnt(2)
	ds_write2_b32 v51, v40, v41 offset0:56 offset1:122
	s_waitcnt vmcnt(0)
	ds_write2_b32 v51, v42, v2 offset0:188 offset1:254
	s_waitcnt lgkmcnt(0)
	ds_read2_b32 v[38:39], v13 offset1:8
	ds_read2_b32 v[40:41], v13 offset0:33 offset1:41
	ds_read2_b32 v[42:43], v13 offset0:66 offset1:74
	ds_read2_b32 v[44:45], v13 offset0:99 offset1:107
	ds_read2_b32 v[46:47], v13 offset0:132 offset1:140
	ds_read2_b32 v[54:55], v13 offset0:165 offset1:173
	ds_read2_b32 v[56:57], v13 offset0:198 offset1:206
	ds_read2_b32 v[58:59], v13 offset0:231 offset1:239
	v_or_b32_e32 v37, s4, v10
	v_lshl_add_u64 v[60:61], s[20:21], 0, v[6:7]
	v_lshlrev_b32_e32 v62, 9, v37
	v_mov_b32_e32 v63, v7
	v_lshl_add_u64 v[62:63], v[60:61], 0, v[62:63]
	s_waitcnt lgkmcnt(6)
	v_cvt_pk_bf16_f32 v2, v38, v40
	s_waitcnt lgkmcnt(4)
	v_cvt_pk_bf16_f32 v3, v42, v44
	s_waitcnt lgkmcnt(2)
	v_cvt_pk_bf16_f32 v4, v46, v54
	s_waitcnt lgkmcnt(0)
	v_cvt_pk_bf16_f32 v5, v56, v58
	global_store_dwordx4 v[62:63], v[2:5], off nt
	v_or_b32_e32 v37, s4, v12
	v_lshlrev_b32_e32 v38, 9, v37
	v_cvt_pk_bf16_f32 v2, v39, v41
	v_cvt_pk_bf16_f32 v3, v43, v45
	v_cvt_pk_bf16_f32 v4, v47, v55
	v_cvt_pk_bf16_f32 v5, v57, v59
	ds_read2_b32 v[40:41], v13 offset0:16 offset1:24
	ds_read2_b32 v[42:43], v13 offset0:49 offset1:57
	ds_read2_b32 v[44:45], v13 offset0:82 offset1:90
	ds_read2_b32 v[46:47], v13 offset0:115 offset1:123
	ds_read2_b32 v[54:55], v13 offset0:148 offset1:156
	ds_read2_b32 v[56:57], v13 offset0:181 offset1:189
	ds_read2_b32 v[58:59], v13 offset0:214 offset1:222
	ds_read2_b32 v[62:63], v13 offset0:247 offset1:255
	v_mov_b32_e32 v39, v7
	v_lshl_add_u64 v[38:39], v[60:61], 0, v[38:39]
	v_or_b32_e32 v37, s4, v14
	global_store_dwordx4 v[38:39], v[2:5], off nt
	v_lshlrev_b32_e32 v38, 9, v37
	v_mov_b32_e32 v39, v7
	v_lshl_add_u64 v[38:39], v[60:61], 0, v[38:39]
	v_or_b32_e32 v37, s4, v16
	s_waitcnt lgkmcnt(6)
	v_cvt_pk_bf16_f32 v2, v40, v42
	s_waitcnt lgkmcnt(4)
	v_cvt_pk_bf16_f32 v3, v44, v46
	s_waitcnt lgkmcnt(2)
	v_cvt_pk_bf16_f32 v4, v54, v56
	s_waitcnt lgkmcnt(0)
	v_cvt_pk_bf16_f32 v5, v58, v62
	global_store_dwordx4 v[38:39], v[2:5], off nt
	v_lshlrev_b32_e32 v38, 9, v37
	v_mov_b32_e32 v39, v7
	v_lshl_add_u64 v[38:39], v[60:61], 0, v[38:39]
	v_cvt_pk_bf16_f32 v2, v41, v43
	v_cvt_pk_bf16_f32 v3, v45, v47
	v_cvt_pk_bf16_f32 v4, v55, v57
	v_cvt_pk_bf16_f32 v5, v59, v63
	global_store_dwordx4 v[38:39], v[2:5], off nt
	s_waitcnt lgkmcnt(0)
	s_mov_b64 s[4:5], 0
.LBB0_17:
	s_andn2_b64 vcc, exec, s[4:5]
	s_cbranch_vccnz .LBB0_19
	s_and_b32 s4, s31, 0x3fc0
	s_addk_i32 s4, 0xd500
	s_and_b32 s20, s27, 0x3e0
	v_or_b32_e32 v2, s4, v9
	s_lshl_b32 s18, s20, 2
	s_waitcnt lgkmcnt(1)
	v_mov_b32_e32 v3, v7
	v_or_b32_e32 v40, 2, v2
	v_mov_b32_e32 v41, v7
	v_or_b32_e32 v42, 4, v2
	v_mov_b32_e32 v43, v7
	v_or_b32_e32 v44, 6, v2
	v_mov_b32_e32 v45, v7
	v_or_b32_e32 v46, 8, v2
	v_mov_b32_e32 v47, v7
	v_or_b32_e32 v54, 10, v2
	v_mov_b32_e32 v55, v7
	v_or_b32_e32 v56, 12, v2
	v_mov_b32_e32 v57, v7
	v_or_b32_e32 v58, 14, v2
	v_mov_b32_e32 v59, v7
	s_waitcnt lgkmcnt(0)
	v_lshl_add_u64 v[4:5], v[26:27], 0, s[18:19]
	v_lshlrev_b64 v[38:39], 12, v[2:3]
	v_lshlrev_b64 v[40:41], 12, v[40:41]
	v_lshlrev_b64 v[42:43], 12, v[42:43]
	v_lshlrev_b64 v[44:45], 12, v[44:45]
	v_lshlrev_b64 v[46:47], 12, v[46:47]
	v_lshlrev_b64 v[54:55], 12, v[54:55]
	v_lshlrev_b64 v[56:57], 12, v[56:57]
	v_lshlrev_b64 v[58:59], 12, v[58:59]
	v_lshl_add_u64 v[38:39], v[4:5], 0, v[38:39]
	v_lshl_add_u64 v[40:41], v[4:5], 0, v[40:41]
	v_lshl_add_u64 v[42:43], v[4:5], 0, v[42:43]
	v_lshl_add_u64 v[44:45], v[4:5], 0, v[44:45]
	v_lshl_add_u64 v[46:47], v[4:5], 0, v[46:47]
	v_lshl_add_u64 v[54:55], v[4:5], 0, v[54:55]
	v_lshl_add_u64 v[56:57], v[4:5], 0, v[56:57]
	v_lshl_add_u64 v[58:59], v[4:5], 0, v[58:59]
	global_load_dword v37, v[38:39], off nt
	global_load_dword v53, v[40:41], off nt
	global_load_dword v60, v[42:43], off nt
	global_load_dword v61, v[44:45], off nt
	global_load_dword v62, v[46:47], off nt
	global_load_dword v63, v[54:55], off nt
	global_load_dword v64, v[56:57], off nt
	global_load_dword v65, v[58:59], off nt
	v_or_b32_e32 v38, 16, v2
	v_mov_b32_e32 v39, v7
	v_or_b32_e32 v40, 18, v2
	v_mov_b32_e32 v41, v7
	v_or_b32_e32 v42, 20, v2
	v_mov_b32_e32 v43, v7
	v_or_b32_e32 v44, 22, v2
	v_mov_b32_e32 v45, v7
	v_or_b32_e32 v46, 24, v2
	v_mov_b32_e32 v47, v7
	v_or_b32_e32 v54, 26, v2
	v_mov_b32_e32 v55, v7
	v_or_b32_e32 v56, 28, v2
	v_mov_b32_e32 v57, v7
	v_or_b32_e32 v58, 30, v2
	v_mov_b32_e32 v59, v7
	v_lshlrev_b64 v[38:39], 12, v[38:39]
	v_lshlrev_b64 v[40:41], 12, v[40:41]
	v_lshlrev_b64 v[42:43], 12, v[42:43]
	v_lshlrev_b64 v[44:45], 12, v[44:45]
	v_lshlrev_b64 v[46:47], 12, v[46:47]
	v_lshlrev_b64 v[54:55], 12, v[54:55]
	v_lshlrev_b64 v[56:57], 12, v[56:57]
	v_lshlrev_b64 v[58:59], 12, v[58:59]
; #define LAS __attribute__((address_space(3)))
; __device__ __forceinline__ unsigned cvt_pk_bf16(float lo, float hi) { unsigned r; asm("v_cvt_pk_bf16_f32 %0, %1, %2" : "=v"(r) : "v"(lo), "v"(hi)); return r; }
; __device__ __forceinline__ void transpose_item(const float* W, int K, int N, bf16_t* WT, int ldt, int k0, int n0, int drow0, LAS float* scr, int lane,
;                                                const float* gam = nullptr, const float* bet = nullptr, float* csp = nullptr, float* bcp = nullptr) {
;     float tv[32];
; #pragma unroll
;     for (int i = 0; i < 32; ++i) tv[i] = __builtin_nontemporal_load(W + (size_t)(k0 + 2 * i + (lane >> 5)) * N + n0 + (lane & 31));
; #pragma unroll
;     for (int i = 0; i < 32; ++i) scr[(2 * i + (lane >> 5)) * 33 + (lane & 31)] = tv[i];
;     asm volatile("s_waitcnt lgkmcnt(0)" ::: "memory");
;     const int c = lane & 7;
;     float ge[8], be[8];
; #pragma unroll
;     for (int e = 0; e < 8; ++e) { ge[e] = gam ? gam[k0 + 8 * c + e] : 1.f; be[e] = gam ? bet[k0 + 8 * c + e] : 0.f; }
; #pragma unroll
;     for (int j = 0; j < 4; ++j) { const int n = (lane >> 3) + 8 * j; const LAS float* sp = scr + (8 * c) * 33 + n;
;         float w[8];
; #pragma unroll
;         for (int e = 0; e < 8; ++e) w[e] = sp[e * 33];
;         u32x4 o; o.x = cvt_pk_bf16(w[0] * ge[0], w[1] * ge[1]); o.y = cvt_pk_bf16(w[2] * ge[2], w[3] * ge[3]); o.z = cvt_pk_bf16(w[4] * ge[4], w[5] * ge[5]); o.w = cvt_pk_bf16(w[6] * ge[6], w[7] * ge[7]);
;         *(u32x4*)(WT + (size_t)(drow0 + n) * ldt + k0 + 8 * c) = o;
	v_lshl_add_u64 v[38:39], v[4:5], 0, v[38:39]
	v_lshl_add_u64 v[40:41], v[4:5], 0, v[40:41]
	v_lshl_add_u64 v[42:43], v[4:5], 0, v[42:43]
	v_lshl_add_u64 v[44:45], v[4:5], 0, v[44:45]
	v_lshl_add_u64 v[46:47], v[4:5], 0, v[46:47]
	v_lshl_add_u64 v[54:55], v[4:5], 0, v[54:55]
	v_lshl_add_u64 v[56:57], v[4:5], 0, v[56:57]
	v_lshl_add_u64 v[58:59], v[4:5], 0, v[58:59]
	global_load_dword v66, v[38:39], off nt
	global_load_dword v67, v[40:41], off nt
	global_load_dword v68, v[42:43], off nt
	global_load_dword v69, v[44:45], off nt
	global_load_dword v70, v[46:47], off nt
	global_load_dword v71, v[54:55], off nt
	global_load_dword v72, v[56:57], off nt
	global_load_dword v73, v[58:59], off nt
	v_or_b32_e32 v38, 32, v2
	v_mov_b32_e32 v39, v7
	v_or_b32_e32 v40, 34, v2
	v_mov_b32_e32 v41, v7
	v_or_b32_e32 v42, 36, v2
	v_mov_b32_e32 v43, v7
	v_or_b32_e32 v44, 38, v2
	v_mov_b32_e32 v45, v7
	v_or_b32_e32 v46, 40, v2
	v_mov_b32_e32 v47, v7
	v_or_b32_e32 v54, 42, v2
	v_mov_b32_e32 v55, v7
	v_or_b32_e32 v56, 44, v2
	v_mov_b32_e32 v57, v7
	v_or_b32_e32 v58, 46, v2
	v_mov_b32_e32 v59, v7
	v_lshlrev_b64 v[38:39], 12, v[38:39]
	v_lshlrev_b64 v[40:41], 12, v[40:41]
	v_lshlrev_b64 v[42:43], 12, v[42:43]
	v_lshlrev_b64 v[44:45], 12, v[44:45]
	v_lshlrev_b64 v[46:47], 12, v[46:47]
	v_lshlrev_b64 v[54:55], 12, v[54:55]
	v_lshlrev_b64 v[56:57], 12, v[56:57]
	v_lshlrev_b64 v[58:59], 12, v[58:59]
	v_lshl_add_u64 v[38:39], v[4:5], 0, v[38:39]
	v_lshl_add_u64 v[40:41], v[4:5], 0, v[40:41]
	v_lshl_add_u64 v[42:43], v[4:5], 0, v[42:43]
	v_lshl_add_u64 v[44:45], v[4:5], 0, v[44:45]
	v_lshl_add_u64 v[46:47], v[4:5], 0, v[46:47]
	v_lshl_add_u64 v[54:55], v[4:5], 0, v[54:55]
	v_lshl_add_u64 v[56:57], v[4:5], 0, v[56:57]
	v_lshl_add_u64 v[58:59], v[4:5], 0, v[58:59]
	global_load_dword v74, v[38:39], off nt
	global_load_dword v75, v[40:41], off nt
	global_load_dword v76, v[42:43], off nt
	global_load_dword v77, v[44:45], off nt
	global_load_dword v78, v[46:47], off nt
	global_load_dword v79, v[54:55], off nt
	global_load_dword v80, v[56:57], off nt
	s_nop 0
	global_load_dword v58, v[58:59], off nt
	v_or_b32_e32 v38, 48, v2
	v_mov_b32_e32 v39, v7
	v_or_b32_e32 v40, 50, v2
	v_mov_b32_e32 v41, v7
	v_or_b32_e32 v42, 52, v2
	v_mov_b32_e32 v43, v7
	v_or_b32_e32 v44, 54, v2
	v_or_b32_e32 v46, 56, v2
	v_or_b32_e32 v54, 58, v2
	v_or_b32_e32 v56, 60, v2
	v_or_b32_e32 v2, 62, v2
	v_lshlrev_b64 v[38:39], 12, v[38:39]
	v_lshlrev_b64 v[40:41], 12, v[40:41]
	v_lshlrev_b64 v[42:43], 12, v[42:43]
	v_mov_b32_e32 v45, v7
	v_mov_b32_e32 v47, v7
	v_mov_b32_e32 v55, v7
	v_mov_b32_e32 v57, v7
	v_lshlrev_b64 v[2:3], 12, v[2:3]
	v_lshl_add_u64 v[38:39], v[4:5], 0, v[38:39]
	v_lshl_add_u64 v[40:41], v[4:5], 0, v[40:41]
	v_lshl_add_u64 v[42:43], v[4:5], 0, v[42:43]
	v_lshlrev_b64 v[44:45], 12, v[44:45]
	v_lshlrev_b64 v[46:47], 12, v[46:47]
	v_lshlrev_b64 v[54:55], 12, v[54:55]
	v_lshlrev_b64 v[56:57], 12, v[56:57]
	v_lshl_add_u64 v[2:3], v[4:5], 0, v[2:3]
	v_lshl_add_u64 v[44:45], v[4:5], 0, v[44:45]
	v_lshl_add_u64 v[46:47], v[4:5], 0, v[46:47]
	v_lshl_add_u64 v[54:55], v[4:5], 0, v[54:55]
	v_lshl_add_u64 v[56:57], v[4:5], 0, v[56:57]
	global_load_dword v4, v[38:39], off nt
	global_load_dword v5, v[40:41], off nt
	s_nop 0
	global_load_dword v38, v[42:43], off nt
	global_load_dword v39, v[44:45], off nt
	global_load_dword v40, v[46:47], off nt
	global_load_dword v41, v[54:55], off nt
	s_nop 0
	global_load_dword v42, v[56:57], off nt
	s_nop 0
	global_load_dword v2, v[2:3], off nt
	s_waitcnt vmcnt(30)
	ds_write2_b32 v11, v37, v53 offset1:66
	s_waitcnt vmcnt(28)
	ds_write2_b32 v11, v60, v61 offset0:132 offset1:198
	s_waitcnt vmcnt(26)
	ds_write2_b32 v15, v62, v63 offset0:8 offset1:74
	s_waitcnt vmcnt(24)
	ds_write2_b32 v15, v64, v65 offset0:140 offset1:206
	s_waitcnt vmcnt(22)
	ds_write2_b32 v17, v66, v67 offset0:16 offset1:82
	s_waitcnt vmcnt(20)
	ds_write2_b32 v17, v68, v69 offset0:148 offset1:214
	s_waitcnt vmcnt(18)
	ds_write2_b32 v35, v70, v71 offset0:24 offset1:90
	s_waitcnt vmcnt(16)
	ds_write2_b32 v35, v72, v73 offset0:156 offset1:222
	s_waitcnt vmcnt(14)
	ds_write2_b32 v48, v74, v75 offset0:32 offset1:98
	s_waitcnt vmcnt(12)
	ds_write2_b32 v48, v76, v77 offset0:164 offset1:230
	s_waitcnt vmcnt(10)
	ds_write2_b32 v49, v78, v79 offset0:40 offset1:106
	s_waitcnt vmcnt(8)
	ds_write2_b32 v49, v80, v58 offset0:172 offset1:238
	s_waitcnt vmcnt(6)
	ds_write2_b32 v50, v4, v5 offset0:48 offset1:114
	s_waitcnt vmcnt(4)
	ds_write2_b32 v50, v38, v39 offset0:180 offset1:246
	s_waitcnt vmcnt(2)
	ds_write2_b32 v51, v40, v41 offset0:56 offset1:122
	s_waitcnt vmcnt(0)
	ds_write2_b32 v51, v42, v2 offset0:188 offset1:254
	s_waitcnt lgkmcnt(0)
	ds_read2_b32 v[38:39], v13 offset1:8
	ds_read2_b32 v[40:41], v13 offset0:33 offset1:41
	ds_read2_b32 v[42:43], v13 offset0:66 offset1:74
	ds_read2_b32 v[44:45], v13 offset0:99 offset1:107
	ds_read2_b32 v[46:47], v13 offset0:132 offset1:140
	ds_read2_b32 v[54:55], v13 offset0:165 offset1:173
	ds_read2_b32 v[56:57], v13 offset0:198 offset1:206
	ds_read2_b32 v[58:59], v13 offset0:231 offset1:239
	s_mov_b32 s5, s19
	v_or_b32_e32 v37, s20, v10
	v_lshl_add_u64 v[60:61], s[4:5], 1, v[18:19]
	v_lshlrev_b32_e32 v62, 13, v37
	v_mov_b32_e32 v63, v7
	v_lshl_add_u64 v[62:63], v[60:61], 0, v[62:63]
	s_waitcnt lgkmcnt(6)
	v_cvt_pk_bf16_f32 v2, v38, v40
	s_waitcnt lgkmcnt(4)
	v_cvt_pk_bf16_f32 v3, v42, v44
	s_waitcnt lgkmcnt(2)
	v_cvt_pk_bf16_f32 v4, v46, v54
	s_waitcnt lgkmcnt(0)
	v_cvt_pk_bf16_f32 v5, v56, v58
	global_store_dwordx4 v[62:63], v[2:5], off nt
	v_or_b32_e32 v37, s20, v12
	v_lshlrev_b32_e32 v38, 13, v37
	v_cvt_pk_bf16_f32 v2, v39, v41
	v_cvt_pk_bf16_f32 v3, v43, v45
	v_cvt_pk_bf16_f32 v4, v47, v55
	v_cvt_pk_bf16_f32 v5, v57, v59
	ds_read2_b32 v[40:41], v13 offset0:16 offset1:24
	ds_read2_b32 v[42:43], v13 offset0:49 offset1:57
	ds_read2_b32 v[44:45], v13 offset0:82 offset1:90
	ds_read2_b32 v[46:47], v13 offset0:115 offset1:123
	ds_read2_b32 v[54:55], v13 offset0:148 offset1:156
	ds_read2_b32 v[56:57], v13 offset0:181 offset1:189
	ds_read2_b32 v[58:59], v13 offset0:214 offset1:222
	ds_read2_b32 v[62:63], v13 offset0:247 offset1:255
	v_mov_b32_e32 v39, v7
	v_lshl_add_u64 v[38:39], v[60:61], 0, v[38:39]
	v_or_b32_e32 v37, s20, v14
	global_store_dwordx4 v[38:39], v[2:5], off nt
	v_lshlrev_b32_e32 v38, 13, v37
	v_mov_b32_e32 v39, v7
	v_lshl_add_u64 v[38:39], v[60:61], 0, v[38:39]
	v_or_b32_e32 v37, s20, v16
	s_waitcnt lgkmcnt(6)
	v_cvt_pk_bf16_f32 v2, v40, v42
	s_waitcnt lgkmcnt(4)
	v_cvt_pk_bf16_f32 v3, v44, v46
	s_waitcnt lgkmcnt(2)
	v_cvt_pk_bf16_f32 v4, v54, v56
	s_waitcnt lgkmcnt(0)
	v_cvt_pk_bf16_f32 v5, v58, v62
	global_store_dwordx4 v[38:39], v[2:5], off nt
	v_lshlrev_b32_e32 v38, 13, v37
	v_mov_b32_e32 v39, v7
	v_lshl_add_u64 v[38:39], v[60:61], 0, v[38:39]
	v_cvt_pk_bf16_f32 v2, v41, v43
	v_cvt_pk_bf16_f32 v3, v45, v47
	v_cvt_pk_bf16_f32 v4, v55, v57
	v_cvt_pk_bf16_f32 v5, v59, v63
	global_store_dwordx4 v[38:39], v[2:5], off nt
	s_waitcnt lgkmcnt(0)

; #define LAS __attribute__((address_space(3)))
; __device__ __forceinline__ unsigned cvt_pk_bf16(float lo, float hi) { unsigned r; asm("v_cvt_pk_bf16_f32 %0, %1, %2" : "=v"(r) : "v"(lo), "v"(hi)); return r; }
; __device__ __forceinline__ float bf_lo(unsigned w) { return __uint_as_float(w << 16); }
; __device__ __forceinline__ float bf_hi(unsigned w) { return __uint_as_float(w & 0xffff0000u); }
; __device__ __forceinline__ void transpose_item(const float* W, int K, int N, bf16_t* WT, int ldt, int k0, int n0, int drow0, LAS float* scr, int lane,
;                                                const float* gam = nullptr, const float* bet = nullptr, float* csp = nullptr, float* bcp = nullptr) {
;     ...
;     for (int j = 0; j < 4; ++j) { const int n = (lane >> 3) + 8 * j; const LAS float* sp = scr + (8 * c) * 33 + n;
;         float w[8];
; #pragma unroll
;         for (int e = 0; e < 8; ++e) w[e] = sp[e * 33];
;         u32x4 o; o.x = cvt_pk_bf16(w[0] * ge[0], w[1] * ge[1]); o.y = cvt_pk_bf16(w[2] * ge[2], w[3] * ge[3]); o.z = cvt_pk_bf16(w[4] * ge[4], w[5] * ge[5]); o.w = cvt_pk_bf16(w[6] * ge[6], w[7] * ge[7]);
;         *(u32x4*)(WT + (size_t)(drow0 + n) * ldt + k0 + 8 * c) = o;
;         if (gam) {
;             float cs = (bf_lo(o.x) + bf_hi(o.x)) + (bf_lo(o.y) + bf_hi(o.y)) + (bf_lo(o.z) + bf_hi(o.z)) + (bf_lo(o.w) + bf_hi(o.w)), bc = 0.f;
; #pragma unroll
;             for (int e = 0; e < 8; ++e) bc += w[e] * be[e];
;             cs += __shfl_xor(cs, 1); cs += __shfl_xor(cs, 2); cs += __shfl_xor(cs, 4); bc += __shfl_xor(bc, 1); bc += __shfl_xor(bc, 2); bc += __shfl_xor(bc, 4);
;             if (c == 0) { csp[(size_t)(k0 >> 6) * N + n0 + n] = cs; bcp[(size_t)(k0 >> 6) * N + n0 + n] = bc; }
;         }
.LBB0_54:
	ds_read2_b32 v[46:47], v13 offset1:33
	ds_read2_b32 v[44:45], v13 offset0:66 offset1:99
	ds_read2_b32 v[42:43], v13 offset0:132 offset1:165
	ds_read2_b32 v[40:41], v13 offset0:198 offset1:231
	s_lshl_b32 s22, s21, 1
	s_mov_b32 s23, s19
	s_waitcnt vmcnt(0) lgkmcnt(2)
	v_mul_f32_e32 v4, v59, v45
	v_mul_f32_e32 v2, v53, v46
	v_mul_f32_e32 v3, v55, v47
	v_cvt_pk_bf16_f32 v2, v2, v3
	v_mul_f32_e32 v3, v57, v44
	v_cvt_pk_bf16_f32 v3, v3, v4
	s_waitcnt lgkmcnt(1)
	v_mul_f32_e32 v4, v61, v42
	v_mul_f32_e32 v5, v63, v43
	v_cvt_pk_bf16_f32 v4, v4, v5
	s_waitcnt lgkmcnt(0)
	v_mul_f32_e32 v5, v65, v40
	v_mul_f32_e32 v68, v67, v41
	s_lshr_b32 s20, s20, 7
	s_mov_b32 s21, s19
	v_cvt_pk_bf16_f32 v5, v5, v68
	v_or_b32_e32 v68, s18, v10
	v_lshl_add_u64 v[38:39], v[20:21], 0, s[22:23]
	s_lshl_b64 s[20:21], s[20:21], 12
	v_lshlrev_b32_e32 v68, 11, v68
	v_mov_b32_e32 v69, v7
	s_or_b64 s[20:21], s[20:21], s[18:19]
	v_lshl_add_u64 v[68:69], v[38:39], 0, v[68:69]
	s_and_b64 vcc, exec, s[4:5]
	global_store_dwordx4 v[68:69], v[2:5], off nt
	s_cbranch_vccnz .LBB0_58
	v_lshlrev_b32_e32 v68, 16, v2
	v_and_b32_e32 v2, 0xffff0000, v2
	v_lshlrev_b32_e32 v69, 16, v3
	v_and_b32_e32 v3, 0xffff0000, v3
	v_add_f32_e32 v3, v69, v3
	v_lshlrev_b32_e32 v69, 16, v4
	v_and_b32_e32 v4, 0xffff0000, v4
	v_add_f32_e32 v2, v68, v2
	v_add_f32_e32 v4, v69, v4
	v_add_f32_e32 v2, v2, v3
	v_add_f32_e32 v2, v2, v4
	v_and_b32_e32 v4, 64, v52
	v_xor_b32_e32 v3, 1, v52
	v_add_u32_e32 v4, 64, v4
	v_lshlrev_b32_e32 v69, 16, v5
	v_and_b32_e32 v5, 0xffff0000, v5
	v_cmp_lt_i32_e32 vcc, v3, v4
	v_add_f32_e32 v5, v69, v5
	v_fma_f32 v46, v37, v46, 0
	v_cndmask_b32_e32 v3, v52, v3, vcc
	v_fmac_f32_e32 v46, v54, v47
	v_add_f32_e32 v2, v2, v5
	v_lshlrev_b32_e32 v3, 2, v3
	v_fmac_f32_e32 v46, v56, v44
	ds_bpermute_b32 v5, v3, v2
	v_fmac_f32_e32 v46, v58, v45
	v_fmac_f32_e32 v46, v60, v42
	v_fmac_f32_e32 v46, v62, v43
	v_fmac_f32_e32 v46, v64, v40
	s_waitcnt lgkmcnt(0)
	v_add_f32_e32 v2, v2, v5
	v_xor_b32_e32 v5, 2, v52
	v_fmac_f32_e32 v46, v66, v41
	v_cmp_lt_i32_e32 vcc, v5, v4
	ds_bpermute_b32 v3, v3, v46
	s_waitcnt lgkmcnt(0)
	v_add_f32_e32 v41, v46, v3
	v_cndmask_b32_e32 v5, v52, v5, vcc
	v_lshlrev_b32_e32 v5, 2, v5
	ds_bpermute_b32 v40, v5, v2
	ds_bpermute_b32 v5, v5, v41
	s_waitcnt lgkmcnt(1)
	v_add_f32_e32 v2, v2, v40
	v_xor_b32_e32 v40, 4, v52
	v_cmp_lt_i32_e32 vcc, v40, v4
	s_waitcnt lgkmcnt(0)
	v_add_f32_e32 v4, v41, v5
	v_cndmask_b32_e32 v3, v52, v40, vcc
	v_lshlrev_b32_e32 v40, 2, v3
	ds_bpermute_b32 v3, v40, v2
	ds_bpermute_b32 v5, v40, v4
	s_and_saveexec_b64 s[22:23], s[0:1]
	s_cbranch_execz .LBB0_57
	s_waitcnt lgkmcnt(1)
	v_add_f32_e32 v41, v2, v3
	v_mov_b32_e32 v3, s21
	v_or_b32_e32 v2, s20, v10
	v_lshlrev_b64 v[2:3], 2, v[2:3]
	s_waitcnt lgkmcnt(0)
	v_add_f32_e32 v40, v4, v5
	v_lshl_add_u64 v[4:5], s[96:97], 0, v[2:3]
	v_lshl_add_u64 v[2:3], s[40:41], 0, v[2:3]
	global_store_dword v[4:5], v41, off
	global_store_dword v[2:3], v40, off

; #define LAS __attribute__((address_space(3)))
; __device__ __forceinline__ unsigned cvt_pk_bf16(float lo, float hi) { unsigned r; asm("v_cvt_pk_bf16_f32 %0, %1, %2" : "=v"(r) : "v"(lo), "v"(hi)); return r; }
; __device__ __forceinline__ float bf_lo(unsigned w) { return __uint_as_float(w << 16); }
; __device__ __forceinline__ float bf_hi(unsigned w) { return __uint_as_float(w & 0xffff0000u); }
; __device__ __forceinline__ void transpose_item(const float* W, int K, int N, bf16_t* WT, int ldt, int k0, int n0, int drow0, LAS float* scr, int lane,
;                                                const float* gam = nullptr, const float* bet = nullptr, float* csp = nullptr, float* bcp = nullptr) {
;     ...
;     for (int j = 0; j < 4; ++j) { const int n = (lane >> 3) + 8 * j; const LAS float* sp = scr + (8 * c) * 33 + n;
;         float w[8];
; #pragma unroll
;         for (int e = 0; e < 8; ++e) w[e] = sp[e * 33];
;         u32x4 o; o.x = cvt_pk_bf16(w[0] * ge[0], w[1] * ge[1]); o.y = cvt_pk_bf16(w[2] * ge[2], w[3] * ge[3]); o.z = cvt_pk_bf16(w[4] * ge[4], w[5] * ge[5]); o.w = cvt_pk_bf16(w[6] * ge[6], w[7] * ge[7]);
;         *(u32x4*)(WT + (size_t)(drow0 + n) * ldt + k0 + 8 * c) = o;
;         if (gam) {
;             float cs = (bf_lo(o.x) + bf_hi(o.x)) + (bf_lo(o.y) + bf_hi(o.y)) + (bf_lo(o.z) + bf_hi(o.z)) + (bf_lo(o.w) + bf_hi(o.w)), bc = 0.f;
; #pragma unroll
;             for (int e = 0; e < 8; ++e) bc += w[e] * be[e];
;             cs += __shfl_xor(cs, 1); cs += __shfl_xor(cs, 2); cs += __shfl_xor(cs, 4); bc += __shfl_xor(bc, 1); bc += __shfl_xor(bc, 2); bc += __shfl_xor(bc, 4);
;             if (c == 0) { csp[(size_t)(k0 >> 6) * N + n0 + n] = cs; bcp[(size_t)(k0 >> 6) * N + n0 + n] = bc; }
;         }
.LBB0_58:
	ds_read2_b32 v[46:47], v13 offset0:8 offset1:41
	ds_read2_b32 v[44:45], v13 offset0:74 offset1:107
	ds_read2_b32 v[42:43], v13 offset0:140 offset1:173
	ds_read2_b32 v[40:41], v13 offset0:206 offset1:239
	v_mov_b32_e32 v69, v7
	s_waitcnt lgkmcnt(3)
	v_mul_f32_e32 v2, v53, v46
	v_mul_f32_e32 v3, v55, v47
	v_cvt_pk_bf16_f32 v2, v2, v3
	s_waitcnt lgkmcnt(2)
	v_mul_f32_e32 v3, v57, v44
	v_mul_f32_e32 v4, v59, v45
	v_cvt_pk_bf16_f32 v3, v3, v4
	s_waitcnt lgkmcnt(1)
	v_mul_f32_e32 v4, v61, v42
	v_mul_f32_e32 v5, v63, v43
	v_cvt_pk_bf16_f32 v4, v4, v5
	s_waitcnt lgkmcnt(0)
	v_mul_f32_e32 v5, v65, v40
	v_mul_f32_e32 v68, v67, v41
	v_cvt_pk_bf16_f32 v5, v5, v68
	v_or_b32_e32 v68, s18, v12
	v_lshlrev_b32_e32 v68, 11, v68
	v_lshl_add_u64 v[68:69], v[38:39], 0, v[68:69]
	s_and_b64 vcc, exec, s[4:5]
	global_store_dwordx4 v[68:69], v[2:5], off nt
	s_cbranch_vccnz .LBB0_62
	v_lshlrev_b32_e32 v68, 16, v2
	v_and_b32_e32 v2, 0xffff0000, v2
	v_lshlrev_b32_e32 v69, 16, v3
	v_and_b32_e32 v3, 0xffff0000, v3
	v_add_f32_e32 v3, v69, v3
	v_lshlrev_b32_e32 v69, 16, v4
	v_and_b32_e32 v4, 0xffff0000, v4
	v_add_f32_e32 v2, v68, v2
	v_add_f32_e32 v4, v69, v4
	v_add_f32_e32 v2, v2, v3
	v_add_f32_e32 v2, v2, v4
	v_and_b32_e32 v4, 64, v52
	v_xor_b32_e32 v3, 1, v52
	v_add_u32_e32 v4, 64, v4
	v_lshlrev_b32_e32 v69, 16, v5
	v_and_b32_e32 v5, 0xffff0000, v5
	v_cmp_lt_i32_e32 vcc, v3, v4
	v_add_f32_e32 v5, v69, v5
	v_fma_f32 v46, v37, v46, 0
	v_cndmask_b32_e32 v3, v52, v3, vcc
	v_fmac_f32_e32 v46, v54, v47
	v_add_f32_e32 v2, v2, v5
	v_lshlrev_b32_e32 v3, 2, v3
	v_fmac_f32_e32 v46, v56, v44
	ds_bpermute_b32 v5, v3, v2
	v_fmac_f32_e32 v46, v58, v45
	v_fmac_f32_e32 v46, v60, v42
	v_fmac_f32_e32 v46, v62, v43
	v_fmac_f32_e32 v46, v64, v40
	s_waitcnt lgkmcnt(0)
	v_add_f32_e32 v2, v2, v5
	v_xor_b32_e32 v5, 2, v52
	v_fmac_f32_e32 v46, v66, v41
	v_cmp_lt_i32_e32 vcc, v5, v4
	ds_bpermute_b32 v3, v3, v46
	s_waitcnt lgkmcnt(0)
	v_add_f32_e32 v41, v46, v3
	v_cndmask_b32_e32 v5, v52, v5, vcc
	v_lshlrev_b32_e32 v5, 2, v5
	ds_bpermute_b32 v40, v5, v2
	ds_bpermute_b32 v5, v5, v41
	s_waitcnt lgkmcnt(1)
	v_add_f32_e32 v2, v2, v40
	v_xor_b32_e32 v40, 4, v52
	v_cmp_lt_i32_e32 vcc, v40, v4
	s_waitcnt lgkmcnt(0)
	v_add_f32_e32 v4, v41, v5
	v_cndmask_b32_e32 v3, v52, v40, vcc
	v_lshlrev_b32_e32 v40, 2, v3
	ds_bpermute_b32 v3, v40, v2
	ds_bpermute_b32 v5, v40, v4
	s_and_saveexec_b64 s[22:23], s[0:1]
	s_cbranch_execz .LBB0_61
	s_waitcnt lgkmcnt(1)
	v_add_f32_e32 v41, v2, v3
	v_mov_b32_e32 v3, s21
	v_or_b32_e32 v2, s20, v12
	v_lshlrev_b64 v[2:3], 2, v[2:3]
	s_waitcnt lgkmcnt(0)
	v_add_f32_e32 v40, v4, v5
	v_lshl_add_u64 v[4:5], s[96:97], 0, v[2:3]
	v_lshl_add_u64 v[2:3], s[40:41], 0, v[2:3]
	global_store_dword v[4:5], v41, off
	global_store_dword v[2:3], v40, off

; #define LAS __attribute__((address_space(3)))
; __device__ __forceinline__ unsigned cvt_pk_bf16(float lo, float hi) { unsigned r; asm("v_cvt_pk_bf16_f32 %0, %1, %2" : "=v"(r) : "v"(lo), "v"(hi)); return r; }
; __device__ __forceinline__ float bf_lo(unsigned w) { return __uint_as_float(w << 16); }
; __device__ __forceinline__ float bf_hi(unsigned w) { return __uint_as_float(w & 0xffff0000u); }
; __device__ __forceinline__ void transpose_item(const float* W, int K, int N, bf16_t* WT, int ldt, int k0, int n0, int drow0, LAS float* scr, int lane,
;                                                const float* gam = nullptr, const float* bet = nullptr, float* csp = nullptr, float* bcp = nullptr) {
;     ...
;     for (int j = 0; j < 4; ++j) { const int n = (lane >> 3) + 8 * j; const LAS float* sp = scr + (8 * c) * 33 + n;
;         float w[8];
; #pragma unroll
;         for (int e = 0; e < 8; ++e) w[e] = sp[e * 33];
;         u32x4 o; o.x = cvt_pk_bf16(w[0] * ge[0], w[1] * ge[1]); o.y = cvt_pk_bf16(w[2] * ge[2], w[3] * ge[3]); o.z = cvt_pk_bf16(w[4] * ge[4], w[5] * ge[5]); o.w = cvt_pk_bf16(w[6] * ge[6], w[7] * ge[7]);
;         *(u32x4*)(WT + (size_t)(drow0 + n) * ldt + k0 + 8 * c) = o;
;         if (gam) {
;             float cs = (bf_lo(o.x) + bf_hi(o.x)) + (bf_lo(o.y) + bf_hi(o.y)) + (bf_lo(o.z) + bf_hi(o.z)) + (bf_lo(o.w) + bf_hi(o.w)), bc = 0.f;
; #pragma unroll
;             for (int e = 0; e < 8; ++e) bc += w[e] * be[e];
;             cs += __shfl_xor(cs, 1); cs += __shfl_xor(cs, 2); cs += __shfl_xor(cs, 4); bc += __shfl_xor(bc, 1); bc += __shfl_xor(bc, 2); bc += __shfl_xor(bc, 4);
;             if (c == 0) { csp[(size_t)(k0 >> 6) * N + n0 + n] = cs; bcp[(size_t)(k0 >> 6) * N + n0 + n] = bc; }
;         }
.LBB0_62:
	ds_read2_b32 v[46:47], v13 offset0:16 offset1:49
	ds_read2_b32 v[44:45], v13 offset0:82 offset1:115
	ds_read2_b32 v[42:43], v13 offset0:148 offset1:181
	ds_read2_b32 v[40:41], v13 offset0:214 offset1:247
	v_mov_b32_e32 v69, v7
	s_waitcnt lgkmcnt(3)
	v_mul_f32_e32 v2, v53, v46
	v_mul_f32_e32 v3, v55, v47
	v_cvt_pk_bf16_f32 v2, v2, v3
	s_waitcnt lgkmcnt(2)
	v_mul_f32_e32 v3, v57, v44
	v_mul_f32_e32 v4, v59, v45
	v_cvt_pk_bf16_f32 v3, v3, v4
	s_waitcnt lgkmcnt(1)
	v_mul_f32_e32 v4, v61, v42
	v_mul_f32_e32 v5, v63, v43
	v_cvt_pk_bf16_f32 v4, v4, v5
	s_waitcnt lgkmcnt(0)
	v_mul_f32_e32 v5, v65, v40
	v_mul_f32_e32 v68, v67, v41
	v_cvt_pk_bf16_f32 v5, v5, v68
	v_or_b32_e32 v68, s18, v14
	v_lshlrev_b32_e32 v68, 11, v68
	v_lshl_add_u64 v[68:69], v[38:39], 0, v[68:69]
	s_and_b64 vcc, exec, s[4:5]
	global_store_dwordx4 v[68:69], v[2:5], off nt
	s_cbranch_vccnz .LBB0_66
	v_lshlrev_b32_e32 v68, 16, v2
	v_and_b32_e32 v2, 0xffff0000, v2
	v_lshlrev_b32_e32 v69, 16, v3
	v_and_b32_e32 v3, 0xffff0000, v3
	v_add_f32_e32 v3, v69, v3
	v_lshlrev_b32_e32 v69, 16, v4
	v_and_b32_e32 v4, 0xffff0000, v4
	v_add_f32_e32 v2, v68, v2
	v_add_f32_e32 v4, v69, v4
	v_add_f32_e32 v2, v2, v3
	v_add_f32_e32 v2, v2, v4
	v_and_b32_e32 v4, 64, v52
	v_xor_b32_e32 v3, 1, v52
	v_add_u32_e32 v4, 64, v4
	v_lshlrev_b32_e32 v69, 16, v5
	v_and_b32_e32 v5, 0xffff0000, v5
	v_cmp_lt_i32_e32 vcc, v3, v4
	v_add_f32_e32 v5, v69, v5
	v_fma_f32 v46, v37, v46, 0
	v_cndmask_b32_e32 v3, v52, v3, vcc
	v_fmac_f32_e32 v46, v54, v47
	v_add_f32_e32 v2, v2, v5
	v_lshlrev_b32_e32 v3, 2, v3
	v_fmac_f32_e32 v46, v56, v44
	ds_bpermute_b32 v5, v3, v2
	v_fmac_f32_e32 v46, v58, v45
	v_fmac_f32_e32 v46, v60, v42
	v_fmac_f32_e32 v46, v62, v43
	v_fmac_f32_e32 v46, v64, v40
	s_waitcnt lgkmcnt(0)
	v_add_f32_e32 v2, v2, v5
	v_xor_b32_e32 v5, 2, v52
	v_fmac_f32_e32 v46, v66, v41
	v_cmp_lt_i32_e32 vcc, v5, v4
	ds_bpermute_b32 v3, v3, v46
	s_waitcnt lgkmcnt(0)
	v_add_f32_e32 v41, v46, v3
	v_cndmask_b32_e32 v5, v52, v5, vcc
	v_lshlrev_b32_e32 v5, 2, v5
	ds_bpermute_b32 v40, v5, v2
	ds_bpermute_b32 v5, v5, v41
	s_waitcnt lgkmcnt(1)
	v_add_f32_e32 v2, v2, v40
	v_xor_b32_e32 v40, 4, v52
	v_cmp_lt_i32_e32 vcc, v40, v4
	s_waitcnt lgkmcnt(0)
	v_add_f32_e32 v4, v41, v5
	v_cndmask_b32_e32 v3, v52, v40, vcc
	v_lshlrev_b32_e32 v40, 2, v3
	ds_bpermute_b32 v3, v40, v2
	ds_bpermute_b32 v5, v40, v4
	s_and_saveexec_b64 s[22:23], s[0:1]
	s_cbranch_execz .LBB0_65
	s_waitcnt lgkmcnt(1)
	v_add_f32_e32 v41, v2, v3
	v_mov_b32_e32 v3, s21
	v_or_b32_e32 v2, s20, v14
	v_lshlrev_b64 v[2:3], 2, v[2:3]
	s_waitcnt lgkmcnt(0)
	v_add_f32_e32 v40, v4, v5
	v_lshl_add_u64 v[4:5], s[96:97], 0, v[2:3]
	v_lshl_add_u64 v[2:3], s[40:41], 0, v[2:3]
	global_store_dword v[4:5], v41, off
	global_store_dword v[2:3], v40, off

; #define LAS __attribute__((address_space(3)))
; __device__ __forceinline__ unsigned cvt_pk_bf16(float lo, float hi) { unsigned r; asm("v_cvt_pk_bf16_f32 %0, %1, %2" : "=v"(r) : "v"(lo), "v"(hi)); return r; }
; __device__ __forceinline__ float bf_lo(unsigned w) { return __uint_as_float(w << 16); }
; __device__ __forceinline__ float bf_hi(unsigned w) { return __uint_as_float(w & 0xffff0000u); }
; __device__ __forceinline__ void transpose_item(const float* W, int K, int N, bf16_t* WT, int ldt, int k0, int n0, int drow0, LAS float* scr, int lane,
;                                                const float* gam = nullptr, const float* bet = nullptr, float* csp = nullptr, float* bcp = nullptr) {
;     ...
;     for (int j = 0; j < 4; ++j) { const int n = (lane >> 3) + 8 * j; const LAS float* sp = scr + (8 * c) * 33 + n;
;         float w[8];
; #pragma unroll
;         for (int e = 0; e < 8; ++e) w[e] = sp[e * 33];
;         u32x4 o; o.x = cvt_pk_bf16(w[0] * ge[0], w[1] * ge[1]); o.y = cvt_pk_bf16(w[2] * ge[2], w[3] * ge[3]); o.z = cvt_pk_bf16(w[4] * ge[4], w[5] * ge[5]); o.w = cvt_pk_bf16(w[6] * ge[6], w[7] * ge[7]);
;         *(u32x4*)(WT + (size_t)(drow0 + n) * ldt + k0 + 8 * c) = o;
;         if (gam) {
;             float cs = (bf_lo(o.x) + bf_hi(o.x)) + (bf_lo(o.y) + bf_hi(o.y)) + (bf_lo(o.z) + bf_hi(o.z)) + (bf_lo(o.w) + bf_hi(o.w)), bc = 0.f;
; #pragma unroll
;             for (int e = 0; e < 8; ++e) bc += w[e] * be[e];
;             cs += __shfl_xor(cs, 1); cs += __shfl_xor(cs, 2); cs += __shfl_xor(cs, 4); bc += __shfl_xor(bc, 1); bc += __shfl_xor(bc, 2); bc += __shfl_xor(bc, 4);
;             if (c == 0) { csp[(size_t)(k0 >> 6) * N + n0 + n] = cs; bcp[(size_t)(k0 >> 6) * N + n0 + n] = bc; }
;         }
.LBB0_66:
	ds_read2_b32 v[46:47], v13 offset0:24 offset1:57
	ds_read2_b32 v[44:45], v13 offset0:90 offset1:123
	ds_read2_b32 v[42:43], v13 offset0:156 offset1:189
	ds_read2_b32 v[40:41], v13 offset0:222 offset1:255
	v_mov_b32_e32 v69, v7
	s_waitcnt lgkmcnt(3)
	v_mul_f32_e32 v2, v53, v46
	v_mul_f32_e32 v3, v55, v47
	v_cvt_pk_bf16_f32 v2, v2, v3
	s_waitcnt lgkmcnt(2)
	v_mul_f32_e32 v3, v57, v44
	v_mul_f32_e32 v4, v59, v45
	v_cvt_pk_bf16_f32 v3, v3, v4
	s_waitcnt lgkmcnt(1)
	v_mul_f32_e32 v4, v61, v42
	v_mul_f32_e32 v5, v63, v43
	v_cvt_pk_bf16_f32 v4, v4, v5
	s_waitcnt lgkmcnt(0)
	v_mul_f32_e32 v5, v65, v40
	v_mul_f32_e32 v53, v67, v41
	v_cvt_pk_bf16_f32 v5, v5, v53
	v_or_b32_e32 v53, s18, v16
	v_lshlrev_b32_e32 v68, 11, v53
	v_lshl_add_u64 v[38:39], v[38:39], 0, v[68:69]
	s_and_b64 vcc, exec, s[4:5]
	global_store_dwordx4 v[38:39], v[2:5], off nt
	s_cbranch_vccnz .LBB0_70
	v_lshlrev_b32_e32 v38, 16, v2
	v_and_b32_e32 v2, 0xffff0000, v2
	v_lshlrev_b32_e32 v39, 16, v3
	v_and_b32_e32 v3, 0xffff0000, v3
	v_add_f32_e32 v3, v39, v3
	v_lshlrev_b32_e32 v39, 16, v4
	v_and_b32_e32 v4, 0xffff0000, v4
	v_add_f32_e32 v2, v38, v2
	v_add_f32_e32 v4, v39, v4
	v_add_f32_e32 v2, v2, v3
	v_add_f32_e32 v2, v2, v4
	v_and_b32_e32 v4, 64, v52
	v_xor_b32_e32 v3, 1, v52
	v_add_u32_e32 v4, 64, v4
	v_lshlrev_b32_e32 v39, 16, v5
	v_and_b32_e32 v5, 0xffff0000, v5
	v_cmp_lt_i32_e32 vcc, v3, v4
	v_add_f32_e32 v5, v39, v5
	v_fma_f32 v37, v37, v46, 0
	v_cndmask_b32_e32 v3, v52, v3, vcc
	v_fmac_f32_e32 v37, v54, v47
	v_add_f32_e32 v2, v2, v5
	v_lshlrev_b32_e32 v3, 2, v3
	v_fmac_f32_e32 v37, v56, v44
	ds_bpermute_b32 v5, v3, v2
	v_fmac_f32_e32 v37, v58, v45
	v_fmac_f32_e32 v37, v60, v42
	v_fmac_f32_e32 v37, v62, v43
	v_fmac_f32_e32 v37, v64, v40
	s_waitcnt lgkmcnt(0)
	v_add_f32_e32 v2, v2, v5
	v_xor_b32_e32 v5, 2, v52
	v_fmac_f32_e32 v37, v66, v41
	v_cmp_lt_i32_e32 vcc, v5, v4
	ds_bpermute_b32 v3, v3, v37
	s_waitcnt lgkmcnt(0)
	v_add_f32_e32 v37, v37, v3
	v_cndmask_b32_e32 v5, v52, v5, vcc
	v_lshlrev_b32_e32 v5, 2, v5
	ds_bpermute_b32 v38, v5, v2
	ds_bpermute_b32 v5, v5, v37
	s_waitcnt lgkmcnt(1)
	v_add_f32_e32 v2, v2, v38
	v_xor_b32_e32 v38, 4, v52
	v_cmp_lt_i32_e32 vcc, v38, v4
	s_waitcnt lgkmcnt(0)
	v_add_f32_e32 v4, v37, v5
	v_cndmask_b32_e32 v3, v52, v38, vcc
	v_lshlrev_b32_e32 v38, 2, v3
	ds_bpermute_b32 v3, v38, v2
	ds_bpermute_b32 v5, v38, v4
	s_and_saveexec_b64 s[4:5], s[0:1]
	s_cbranch_execz .LBB0_69
	s_waitcnt lgkmcnt(1)
	v_add_f32_e32 v38, v2, v3
	v_mov_b32_e32 v3, s21
	v_or_b32_e32 v2, s20, v16
	v_lshlrev_b64 v[2:3], 2, v[2:3]
	s_waitcnt lgkmcnt(0)
	v_add_f32_e32 v37, v4, v5
	v_lshl_add_u64 v[4:5], s[96:97], 0, v[2:3]
	v_lshl_add_u64 v[2:3], s[40:41], 0, v[2:3]
	global_store_dword v[4:5], v38, off
	global_store_dword v[2:3], v37, off

; __device__ __forceinline__ void transpose_item(const float* W, int K, int N, bf16_t* WT, int ldt, int k0, int n0, int drow0, LAS float* scr, int lane,
;                                                const float* gam = nullptr, const float* bet = nullptr, float* csp = nullptr, float* bcp = nullptr) {
;     float tv[32];
; #pragma unroll
;     for (int i = 0; i < 32; ++i) tv[i] = __builtin_nontemporal_load(W + (size_t)(k0 + 2 * i + (lane >> 5)) * N + n0 + (lane & 31));
; #pragma unroll
;     for (int i = 0; i < 32; ++i) scr[(2 * i + (lane >> 5)) * 33 + (lane & 31)] = tv[i];
; __device__ __forceinline__ void p0_prologue(const Params& p, const Frame& F0) {
;     ...
;         if (r < 5 * I_SQ) { const int w = r / I_SQ, q = r % I_SQ, kb = q / 32, nb = q % 32;
;             const float* src = w == 0 ? p.in[23] : w == 1 ? p.in[26] : w == 2 ? p.in[27] : w == 3 ? p.in[28] : p.in[29];
;             bf16_t* dst = w == 0 ? Wout_t : w == 1 ? Wq_t : w == 2 ? Wkv_t : w == 3 ? Wkv_t + (size_t)DM * DM : Wo_t;
;             float* csp = (float*)(p.ws + WS_CSP);
;             if (w == 1) transpose_item(src, DM, DM, dst, DM, 64 * kb, 32 * nb, 32 * nb, scr, F.lane, p.in[24], p.in[25], csp, csp + 16 * DM);
;             else transpose_item(src, DM, DM, dst, DM, 64 * kb, 32 * nb, 32 * nb, scr, F.lane);
.LBB0_93:
	s_bfe_u32 s22, s18, 0x40005
	s_and_b32 s18, s27, 0x3e0
	s_lshl_b32 s23, s22, 6
	s_lshl_b32 s24, s18, 2
	s_add_u32 s4, s4, s24
	s_addc_u32 s5, s5, 0
	v_or_b32_e32 v4, s23, v9
	v_mov_b32_e32 v37, v7
	s_waitcnt lgkmcnt(1)
	v_lshl_add_u64 v[2:3], s[4:5], 0, v[36:37]
	v_lshlrev_b32_e32 v4, 12, v4
	s_waitcnt lgkmcnt(0)
	v_mov_b32_e32 v5, v7
	v_lshl_add_u64 v[2:3], v[2:3], 0, v[4:5]
	v_add_co_u32_e32 v4, vcc, s14, v2
	s_mov_b32 s4, 0x22000
	s_nop 0
	v_addc_co_u32_e32 v5, vcc, 0, v3, vcc
	v_add_co_u32_e32 v38, vcc, s15, v2
	s_cmp_lg_u32 s39, 1
	s_nop 0
	v_addc_co_u32_e32 v39, vcc, 0, v3, vcc
	v_add_co_u32_e32 v40, vcc, s63, v2
	s_nop 1
	v_addc_co_u32_e32 v41, vcc, 0, v3, vcc
	v_add_co_u32_e32 v42, vcc, s64, v2
	s_nop 1
	v_addc_co_u32_e32 v43, vcc, 0, v3, vcc
	v_add_co_u32_e32 v44, vcc, s65, v2
	s_nop 1
	v_addc_co_u32_e32 v45, vcc, 0, v3, vcc
	v_add_co_u32_e32 v46, vcc, s66, v2
	s_nop 1
	v_addc_co_u32_e32 v47, vcc, 0, v3, vcc
	v_add_co_u32_e32 v54, vcc, s67, v2
	s_nop 1
	v_addc_co_u32_e32 v55, vcc, 0, v3, vcc
	global_load_dword v37, v[2:3], off nt
	global_load_dword v53, v[4:5], off nt
	global_load_dword v58, v[38:39], off nt
	global_load_dword v59, v[40:41], off nt
	global_load_dword v60, v[42:43], off nt
	global_load_dword v61, v[44:45], off nt
	global_load_dword v62, v[46:47], off nt
	global_load_dword v63, v[54:55], off nt
	v_add_co_u32_e32 v4, vcc, s68, v2
	s_nop 1
	v_addc_co_u32_e32 v5, vcc, 0, v3, vcc
	v_add_co_u32_e32 v38, vcc, s69, v2
	s_nop 1
	v_addc_co_u32_e32 v39, vcc, 0, v3, vcc
	v_add_co_u32_e32 v40, vcc, s70, v2
	s_nop 1
	v_addc_co_u32_e32 v41, vcc, 0, v3, vcc
	v_add_co_u32_e32 v42, vcc, s71, v2
	s_nop 1
	v_addc_co_u32_e32 v43, vcc, 0, v3, vcc
	v_add_co_u32_e32 v44, vcc, s72, v2
	s_nop 1
	v_addc_co_u32_e32 v45, vcc, 0, v3, vcc
	v_add_co_u32_e32 v46, vcc, s73, v2
	s_nop 1
	v_addc_co_u32_e32 v47, vcc, 0, v3, vcc
	v_add_co_u32_e32 v54, vcc, s74, v2
	s_nop 1
	v_addc_co_u32_e32 v55, vcc, 0, v3, vcc
	v_add_co_u32_e32 v56, vcc, s75, v2
	s_nop 1
	v_addc_co_u32_e32 v57, vcc, 0, v3, vcc
	global_load_dword v64, v[4:5], off nt
	global_load_dword v65, v[38:39], off nt
	global_load_dword v66, v[40:41], off nt
	global_load_dword v67, v[42:43], off nt
	global_load_dword v68, v[44:45], off nt
	global_load_dword v69, v[46:47], off nt
	global_load_dword v70, v[54:55], off nt
	global_load_dword v71, v[56:57], off nt
	v_add_co_u32_e32 v4, vcc, s94, v2
	s_nop 1
	v_addc_co_u32_e32 v5, vcc, 0, v3, vcc
	v_add_co_u32_e32 v38, vcc, s4, v2
	s_mov_b32 s4, 0x24000
	s_nop 0
	v_addc_co_u32_e32 v39, vcc, 0, v3, vcc
	v_add_co_u32_e32 v40, vcc, s4, v2
	s_mov_b64 s[4:5], -1
	s_nop 0
	v_addc_co_u32_e32 v41, vcc, 0, v3, vcc
	v_add_co_u32_e32 v42, vcc, s12, v2
	s_nop 1
	v_addc_co_u32_e32 v43, vcc, 0, v3, vcc
	v_add_co_u32_e32 v44, vcc, s13, v2
	s_nop 1
	v_addc_co_u32_e32 v45, vcc, 0, v3, vcc
	v_add_co_u32_e32 v46, vcc, s42, v2
	s_nop 1
	v_addc_co_u32_e32 v47, vcc, 0, v3, vcc
	v_add_co_u32_e32 v54, vcc, s43, v2
	s_nop 1
	v_addc_co_u32_e32 v55, vcc, 0, v3, vcc
	v_add_co_u32_e32 v56, vcc, s44, v2
	s_nop 1
	v_addc_co_u32_e32 v57, vcc, 0, v3, vcc
	global_load_dword v72, v[4:5], off nt
	global_load_dword v73, v[38:39], off nt
	global_load_dword v74, v[40:41], off nt
	global_load_dword v75, v[42:43], off nt
	global_load_dword v76, v[44:45], off nt
	global_load_dword v77, v[46:47], off nt
	global_load_dword v78, v[54:55], off nt
	s_nop 0
	global_load_dword v56, v[56:57], off nt
	v_add_co_u32_e32 v4, vcc, s45, v2
	v_or_b32_e32 v57, s18, v12
	s_nop 0
	v_addc_co_u32_e32 v5, vcc, 0, v3, vcc
	v_add_co_u32_e32 v38, vcc, s48, v2
	s_nop 1
	v_addc_co_u32_e32 v39, vcc, 0, v3, vcc
	v_add_co_u32_e32 v40, vcc, s49, v2
	s_nop 1
	v_addc_co_u32_e32 v41, vcc, 0, v3, vcc
	v_add_co_u32_e32 v42, vcc, s60, v2
	s_nop 1
	v_addc_co_u32_e32 v43, vcc, 0, v3, vcc
	v_add_co_u32_e32 v44, vcc, s61, v2
	s_nop 1
	v_addc_co_u32_e32 v45, vcc, 0, v3, vcc
	v_add_co_u32_e32 v46, vcc, s95, v2
	s_nop 1
	v_addc_co_u32_e32 v47, vcc, 0, v3, vcc
	v_add_co_u32_e32 v54, vcc, s3, v2
	s_nop 1
	v_addc_co_u32_e32 v55, vcc, 0, v3, vcc
	v_add_co_u32_e32 v2, vcc, s37, v2
	s_nop 1
	v_addc_co_u32_e32 v3, vcc, 0, v3, vcc
	global_load_dword v4, v[4:5], off nt
	s_nop 0
	global_load_dword v5, v[38:39], off nt
	s_nop 0
	global_load_dword v38, v[40:41], off nt
	global_load_dword v39, v[42:43], off nt
	s_nop 0
	global_load_dword v40, v[44:45], off nt
	global_load_dword v41, v[46:47], off nt
	global_load_dword v42, v[54:55], off nt
	s_nop 0
	global_load_dword v2, v[2:3], off nt
	s_waitcnt vmcnt(30)
	ds_write2_b32 v11, v37, v53 offset1:66
	s_waitcnt vmcnt(28)
	ds_write2_b32 v11, v58, v59 offset0:132 offset1:198
	s_waitcnt vmcnt(26)
	ds_write2_b32 v15, v60, v61 offset0:8 offset1:74
	s_waitcnt vmcnt(24)
	ds_write2_b32 v15, v62, v63 offset0:140 offset1:206
	s_waitcnt vmcnt(22)
	ds_write2_b32 v17, v64, v65 offset0:16 offset1:82
	s_waitcnt vmcnt(20)
	ds_write2_b32 v17, v66, v67 offset0:148 offset1:214
	s_waitcnt vmcnt(18)
	ds_write2_b32 v35, v68, v69 offset0:24 offset1:90
	s_waitcnt vmcnt(16)
	ds_write2_b32 v35, v70, v71 offset0:156 offset1:222
	s_waitcnt vmcnt(14)
	ds_write2_b32 v48, v72, v73 offset0:32 offset1:98
	s_waitcnt vmcnt(12)
	ds_write2_b32 v48, v74, v75 offset0:164 offset1:230
	s_waitcnt vmcnt(10)
	ds_write2_b32 v49, v76, v77 offset0:40 offset1:106
	s_waitcnt vmcnt(8)
	ds_write2_b32 v49, v78, v56 offset0:172 offset1:238
	s_waitcnt vmcnt(6)
	ds_write2_b32 v50, v4, v5 offset0:48 offset1:114
	s_waitcnt vmcnt(4)
	ds_write2_b32 v50, v38, v39 offset0:180 offset1:246
	s_waitcnt vmcnt(2)
	ds_write2_b32 v51, v40, v41 offset0:56 offset1:122
	s_waitcnt vmcnt(0)
	ds_write2_b32 v51, v42, v2 offset0:188 offset1:254
	v_or_b32_e32 v62, s18, v10
	v_or_b32_e32 v53, s18, v14
	v_or_b32_e32 v37, s18, v16
	s_cbranch_scc0 .LBB0_95
; #define LAS __attribute__((address_space(3)))
; __device__ __forceinline__ unsigned cvt_pk_bf16(float lo, float hi) { unsigned r; asm("v_cvt_pk_bf16_f32 %0, %1, %2" : "=v"(r) : "v"(lo), "v"(hi)); return r; }
; __device__ __forceinline__ void transpose_item(const float* W, int K, int N, bf16_t* WT, int ldt, int k0, int n0, int drow0, LAS float* scr, int lane,
;                                                const float* gam = nullptr, const float* bet = nullptr, float* csp = nullptr, float* bcp = nullptr) {
;     ...
;     for (int j = 0; j < 4; ++j) { const int n = (lane >> 3) + 8 * j; const LAS float* sp = scr + (8 * c) * 33 + n;
;         float w[8];
; #pragma unroll
;         for (int e = 0; e < 8; ++e) w[e] = sp[e * 33];
;         u32x4 o; o.x = cvt_pk_bf16(w[0] * ge[0], w[1] * ge[1]); o.y = cvt_pk_bf16(w[2] * ge[2], w[3] * ge[3]); o.z = cvt_pk_bf16(w[4] * ge[4], w[5] * ge[5]); o.w = cvt_pk_bf16(w[6] * ge[6], w[7] * ge[7]);
;         *(u32x4*)(WT + (size_t)(drow0 + n) * ldt + k0 + 8 * c) = o;
	s_waitcnt lgkmcnt(0)
	s_lshl_b32 s4, s23, 1
	ds_read2_b32 v[38:39], v13 offset1:8
	ds_read2_b32 v[40:41], v13 offset0:33 offset1:41
	ds_read2_b32 v[42:43], v13 offset0:66 offset1:74
	ds_read2_b32 v[44:45], v13 offset0:99 offset1:107
	ds_read2_b32 v[46:47], v13 offset0:132 offset1:140
	ds_read2_b32 v[54:55], v13 offset0:165 offset1:173
	ds_read2_b32 v[58:59], v13 offset0:198 offset1:206
	ds_read2_b32 v[60:61], v13 offset0:231 offset1:239
	s_add_u32 s4, s20, s4
	s_addc_u32 s5, s21, 0
	v_lshl_add_u64 v[64:65], s[4:5], 0, v[6:7]
	v_lshlrev_b32_e32 v66, 11, v62
	v_mov_b32_e32 v67, v7
	v_lshl_add_u64 v[66:67], v[64:65], 0, v[66:67]
	s_waitcnt lgkmcnt(6)
	v_cvt_pk_bf16_f32 v2, v38, v40
	s_waitcnt lgkmcnt(4)
	v_cvt_pk_bf16_f32 v3, v42, v44
	s_waitcnt lgkmcnt(2)
	v_cvt_pk_bf16_f32 v4, v46, v54
	s_waitcnt lgkmcnt(0)
	v_cvt_pk_bf16_f32 v5, v58, v60
	global_store_dwordx4 v[66:67], v[2:5], off nt
	v_lshlrev_b32_e32 v38, 11, v57
	s_mov_b64 s[4:5], 0
	v_cvt_pk_bf16_f32 v2, v39, v41
	v_cvt_pk_bf16_f32 v3, v43, v45
	v_cvt_pk_bf16_f32 v4, v47, v55
	v_cvt_pk_bf16_f32 v5, v59, v61
	ds_read2_b32 v[40:41], v13 offset0:16 offset1:24
	ds_read2_b32 v[42:43], v13 offset0:49 offset1:57
	ds_read2_b32 v[44:45], v13 offset0:82 offset1:90
	ds_read2_b32 v[46:47], v13 offset0:115 offset1:123
	ds_read2_b32 v[54:55], v13 offset0:148 offset1:156
	ds_read2_b32 v[58:59], v13 offset0:181 offset1:189
	ds_read2_b32 v[60:61], v13 offset0:214 offset1:222
	ds_read2_b32 v[66:67], v13 offset0:247 offset1:255
	v_mov_b32_e32 v39, v7
	v_lshl_add_u64 v[38:39], v[64:65], 0, v[38:39]
	global_store_dwordx4 v[38:39], v[2:5], off nt
	v_lshlrev_b32_e32 v38, 11, v53
	v_mov_b32_e32 v39, v7
	v_lshl_add_u64 v[38:39], v[64:65], 0, v[38:39]
	s_waitcnt lgkmcnt(6)
	v_cvt_pk_bf16_f32 v2, v40, v42
	s_waitcnt lgkmcnt(4)
	v_cvt_pk_bf16_f32 v3, v44, v46
	s_waitcnt lgkmcnt(2)
	v_cvt_pk_bf16_f32 v4, v54, v58
	s_waitcnt lgkmcnt(0)
	v_cvt_pk_bf16_f32 v5, v60, v66
	global_store_dwordx4 v[38:39], v[2:5], off nt
	v_lshlrev_b32_e32 v38, 11, v37
	v_mov_b32_e32 v39, v7
	v_lshl_add_u64 v[38:39], v[64:65], 0, v[38:39]
	v_cvt_pk_bf16_f32 v2, v41, v43
	v_cvt_pk_bf16_f32 v3, v45, v47
	v_cvt_pk_bf16_f32 v4, v55, v59
	v_cvt_pk_bf16_f32 v5, v61, v67
	global_store_dwordx4 v[38:39], v[2:5], off nt
	s_waitcnt lgkmcnt(0)
